# GEMM K-loop heads aligned to 64 bytes (on top of prefetch fix and attention max3)
# speedup vs baseline: 1.0006x; 1.0006x over previous
.LBB0_131:
	s_ashr_i32 s23, s22, 31
	s_lshl_b64 s[24:25], s[22:23], 20
	s_add_u32 s24, s60, s24
	s_addc_u32 s25, s61, s25
	s_and_b64 s[26:27], s[0:1], exec
	s_cselect_b32 s23, s25, s35
	s_cselect_b32 s48, s24, s34
	s_ashr_i32 s21, s20, 31
	s_lshl_b64 s[26:27], s[20:21], 20
	s_add_u32 s26, s88, s26
	s_addc_u32 s27, s89, s27
	s_and_b64 s[56:57], s[0:1], exec
	s_cselect_b32 s21, s27, s31
	s_cselect_b32 s49, s26, s30
	v_lshl_add_u32 v152, s28, 8, v160
	s_add_u32 s28, s34, 0x80080
	s_addc_u32 s29, s35, 0
	v_ashrrev_i32_e32 v153, 31, v152
	s_add_u32 s51, s30, 0x100
	v_mov_b32_e32 v0, 0
	v_lshl_add_u64 v[154:155], v[152:153], 3, s[6:7]
	s_addc_u32 s53, s31, 0
	s_mov_b32 s55, -2
	v_mov_b32_e32 v1, v0
	v_mov_b32_e32 v2, v0
	v_mov_b32_e32 v3, v0
	v_mov_b32_e32 v4, v0
	v_mov_b32_e32 v5, v0
	v_mov_b32_e32 v6, v0
	v_mov_b32_e32 v7, v0
	v_mov_b32_e32 v16, v0
	v_mov_b32_e32 v17, v0
	v_mov_b32_e32 v18, v0
	v_mov_b32_e32 v19, v0
	v_mov_b32_e32 v20, v0
	v_mov_b32_e32 v21, v0
	v_mov_b32_e32 v22, v0
	v_mov_b32_e32 v23, v0
	v_mov_b32_e32 v32, v0
	v_mov_b32_e32 v33, v0
	v_mov_b32_e32 v34, v0
	v_mov_b32_e32 v35, v0
	v_mov_b32_e32 v36, v0
	v_mov_b32_e32 v37, v0
	v_mov_b32_e32 v38, v0
	v_mov_b32_e32 v39, v0
	v_mov_b32_e32 v48, v0
	v_mov_b32_e32 v49, v0
	v_mov_b32_e32 v50, v0
	v_mov_b32_e32 v51, v0
	v_mov_b32_e32 v52, v0
	v_mov_b32_e32 v53, v0
	v_mov_b32_e32 v54, v0
	v_mov_b32_e32 v55, v0
	v_mov_b32_e32 v8, v0
	v_mov_b32_e32 v9, v0
	v_mov_b32_e32 v10, v0
	v_mov_b32_e32 v11, v0
	v_mov_b32_e32 v12, v0
	v_mov_b32_e32 v13, v0
	v_mov_b32_e32 v14, v0
	v_mov_b32_e32 v15, v0
	v_mov_b32_e32 v24, v0
	v_mov_b32_e32 v25, v0
	v_mov_b32_e32 v26, v0
	v_mov_b32_e32 v27, v0
	v_mov_b32_e32 v28, v0
	v_mov_b32_e32 v29, v0
	v_mov_b32_e32 v30, v0
	v_mov_b32_e32 v31, v0
	v_mov_b32_e32 v40, v0
	v_mov_b32_e32 v41, v0
	v_mov_b32_e32 v42, v0
	v_mov_b32_e32 v43, v0
	v_mov_b32_e32 v44, v0
	v_mov_b32_e32 v45, v0
	v_mov_b32_e32 v46, v0
	v_mov_b32_e32 v47, v0
	v_mov_b32_e32 v56, v0
	v_mov_b32_e32 v57, v0
	v_mov_b32_e32 v58, v0
	v_mov_b32_e32 v59, v0
	v_mov_b32_e32 v60, v0
	v_mov_b32_e32 v61, v0
	v_mov_b32_e32 v62, v0
	v_mov_b32_e32 v63, v0
	v_mov_b32_e32 v64, v0
	v_mov_b32_e32 v65, v0
	v_mov_b32_e32 v66, v0
	v_mov_b32_e32 v67, v0
	v_mov_b32_e32 v68, v0
	v_mov_b32_e32 v69, v0
	v_mov_b32_e32 v70, v0
	v_mov_b32_e32 v71, v0
	v_mov_b32_e32 v80, v0
	v_mov_b32_e32 v81, v0
	v_mov_b32_e32 v82, v0
	v_mov_b32_e32 v83, v0
	v_mov_b32_e32 v84, v0
	v_mov_b32_e32 v85, v0
	v_mov_b32_e32 v86, v0
	v_mov_b32_e32 v87, v0
	v_mov_b32_e32 v96, v0
	v_mov_b32_e32 v97, v0
	v_mov_b32_e32 v98, v0
	v_mov_b32_e32 v99, v0
	v_mov_b32_e32 v100, v0
	v_mov_b32_e32 v101, v0
	v_mov_b32_e32 v102, v0
	v_mov_b32_e32 v103, v0
	v_mov_b32_e32 v112, v0
	v_mov_b32_e32 v113, v0
	v_mov_b32_e32 v114, v0
	v_mov_b32_e32 v115, v0
	v_mov_b32_e32 v116, v0
	v_mov_b32_e32 v117, v0
	v_mov_b32_e32 v118, v0
	v_mov_b32_e32 v119, v0
	v_mov_b32_e32 v72, v0
	v_mov_b32_e32 v73, v0
	v_mov_b32_e32 v74, v0
	v_mov_b32_e32 v75, v0
	v_mov_b32_e32 v76, v0
	v_mov_b32_e32 v77, v0
	v_mov_b32_e32 v78, v0
	v_mov_b32_e32 v79, v0
	v_mov_b32_e32 v88, v0
	v_mov_b32_e32 v89, v0
	v_mov_b32_e32 v90, v0
	v_mov_b32_e32 v91, v0
	v_mov_b32_e32 v92, v0
	v_mov_b32_e32 v93, v0
	v_mov_b32_e32 v94, v0
	v_mov_b32_e32 v95, v0
	v_mov_b32_e32 v104, v0
	v_mov_b32_e32 v105, v0
	v_mov_b32_e32 v106, v0
	v_mov_b32_e32 v107, v0
	v_mov_b32_e32 v108, v0
	v_mov_b32_e32 v109, v0
	v_mov_b32_e32 v110, v0
	v_mov_b32_e32 v111, v0
	v_mov_b32_e32 v120, v0
	v_mov_b32_e32 v121, v0
	v_mov_b32_e32 v122, v0
	v_mov_b32_e32 v123, v0
	v_mov_b32_e32 v124, v0
	v_mov_b32_e32 v125, v0
	v_mov_b32_e32 v126, v0
	v_mov_b32_e32 v127, v0
	s_branch .LBB0_133
	.p2align 6

.LBB0_236:
	s_add_u32 s48, s24, 0x100
	v_mov_b32_e32 v0, 0
	s_addc_u32 s49, s25, 0
	s_mov_b32 s51, -2
	s_waitcnt lgkmcnt(0)
	v_mov_b32_e32 v1, v0
	v_mov_b32_e32 v2, v0
	v_mov_b32_e32 v3, v0
	v_mov_b32_e32 v4, v0
	v_mov_b32_e32 v5, v0
	v_mov_b32_e32 v6, v0
	v_mov_b32_e32 v7, v0
	v_mov_b32_e32 v16, v0
	v_mov_b32_e32 v17, v0
	v_mov_b32_e32 v18, v0
	v_mov_b32_e32 v19, v0
	v_mov_b32_e32 v20, v0
	v_mov_b32_e32 v21, v0
	v_mov_b32_e32 v22, v0
	v_mov_b32_e32 v23, v0
	v_mov_b32_e32 v32, v0
	v_mov_b32_e32 v33, v0
	v_mov_b32_e32 v34, v0
	v_mov_b32_e32 v35, v0
	v_mov_b32_e32 v36, v0
	v_mov_b32_e32 v37, v0
	v_mov_b32_e32 v38, v0
	v_mov_b32_e32 v39, v0
	v_mov_b32_e32 v48, v0
	v_mov_b32_e32 v49, v0
	v_mov_b32_e32 v50, v0
	v_mov_b32_e32 v51, v0
	v_mov_b32_e32 v52, v0
	v_mov_b32_e32 v53, v0
	v_mov_b32_e32 v54, v0
	v_mov_b32_e32 v55, v0
	v_mov_b32_e32 v8, v0
	v_mov_b32_e32 v9, v0
	v_mov_b32_e32 v10, v0
	v_mov_b32_e32 v11, v0
	v_mov_b32_e32 v12, v0
	v_mov_b32_e32 v13, v0
	v_mov_b32_e32 v14, v0
	v_mov_b32_e32 v15, v0
	v_mov_b32_e32 v24, v0
	v_mov_b32_e32 v25, v0
	v_mov_b32_e32 v26, v0
	v_mov_b32_e32 v27, v0
	v_mov_b32_e32 v28, v0
	v_mov_b32_e32 v29, v0
	v_mov_b32_e32 v30, v0
	v_mov_b32_e32 v31, v0
	v_mov_b32_e32 v40, v0
	v_mov_b32_e32 v41, v0
	v_mov_b32_e32 v42, v0
	v_mov_b32_e32 v43, v0
	v_mov_b32_e32 v44, v0
	v_mov_b32_e32 v45, v0
	v_mov_b32_e32 v46, v0
	v_mov_b32_e32 v47, v0
	v_mov_b32_e32 v56, v0
	v_mov_b32_e32 v57, v0
	v_mov_b32_e32 v58, v0
	v_mov_b32_e32 v59, v0
	v_mov_b32_e32 v60, v0
	v_mov_b32_e32 v61, v0
	v_mov_b32_e32 v62, v0
	v_mov_b32_e32 v63, v0
	v_mov_b32_e32 v64, v0
	v_mov_b32_e32 v65, v0
	v_mov_b32_e32 v66, v0
	v_mov_b32_e32 v67, v0
	v_mov_b32_e32 v68, v0
	v_mov_b32_e32 v69, v0
	v_mov_b32_e32 v70, v0
	v_mov_b32_e32 v71, v0
	v_mov_b32_e32 v80, v0
	v_mov_b32_e32 v81, v0
	v_mov_b32_e32 v82, v0
	v_mov_b32_e32 v83, v0
	v_mov_b32_e32 v84, v0
	v_mov_b32_e32 v85, v0
	v_mov_b32_e32 v86, v0
	v_mov_b32_e32 v87, v0
	v_mov_b32_e32 v96, v0
	v_mov_b32_e32 v97, v0
	v_mov_b32_e32 v98, v0
	v_mov_b32_e32 v99, v0
	v_mov_b32_e32 v100, v0
	v_mov_b32_e32 v101, v0
	v_mov_b32_e32 v102, v0
	v_mov_b32_e32 v103, v0
	v_mov_b32_e32 v112, v0
	v_mov_b32_e32 v113, v0
	v_mov_b32_e32 v114, v0
	v_mov_b32_e32 v115, v0
	v_mov_b32_e32 v116, v0
	v_mov_b32_e32 v117, v0
	v_mov_b32_e32 v118, v0
	v_mov_b32_e32 v119, v0
	v_mov_b32_e32 v72, v0
	v_mov_b32_e32 v73, v0
	v_mov_b32_e32 v74, v0
	v_mov_b32_e32 v75, v0
	v_mov_b32_e32 v76, v0
	v_mov_b32_e32 v77, v0
	v_mov_b32_e32 v78, v0
	v_mov_b32_e32 v79, v0
	v_mov_b32_e32 v88, v0
	v_mov_b32_e32 v89, v0
	v_mov_b32_e32 v90, v0
	v_mov_b32_e32 v91, v0
	v_mov_b32_e32 v92, v0
	v_mov_b32_e32 v93, v0
	v_mov_b32_e32 v94, v0
	v_mov_b32_e32 v95, v0
	v_mov_b32_e32 v104, v0
	v_mov_b32_e32 v105, v0
	v_mov_b32_e32 v106, v0
	v_mov_b32_e32 v107, v0
	v_mov_b32_e32 v108, v0
	v_mov_b32_e32 v109, v0
	v_mov_b32_e32 v110, v0
	v_mov_b32_e32 v111, v0
	v_mov_b32_e32 v120, v0
	v_mov_b32_e32 v121, v0
	v_mov_b32_e32 v122, v0
	v_mov_b32_e32 v123, v0
	v_mov_b32_e32 v124, v0
	v_mov_b32_e32 v125, v0
	v_mov_b32_e32 v126, v0
	v_mov_b32_e32 v127, v0
	.p2align 6

.LBB0_330:
	s_ashr_i32 s23, s22, 31
	s_lshl_b64 s[24:25], s[22:23], 20
	s_add_u32 s24, s60, s24
	s_addc_u32 s25, s61, s25
	s_and_b64 s[26:27], s[6:7], exec
	s_cselect_b32 s23, s25, s35
	s_cselect_b32 s46, s24, s34
	s_ashr_i32 s21, s20, 31
	s_lshl_b64 s[26:27], s[20:21], 20
	s_add_u32 s26, s14, s26
	s_addc_u32 s27, s15, s27
	s_and_b64 s[48:49], s[6:7], exec
	s_cselect_b32 s21, s27, s31
	s_cselect_b32 s47, s26, s30
	v_lshl_add_u32 v144, s8, 8, v148
	s_add_u32 s8, s34, 0x80080
	s_addc_u32 s9, s35, 0
	v_ashrrev_i32_e32 v145, 31, v144
	s_add_u32 s48, s30, 0x100
	v_mov_b32_e32 v0, 0
	v_lshl_add_u64 v[146:147], v[144:145], 3, s[16:17]
	s_addc_u32 s49, s31, 0
	s_mov_b32 s51, -2
	v_mov_b32_e32 v1, v0
	v_mov_b32_e32 v2, v0
	v_mov_b32_e32 v3, v0
	v_mov_b32_e32 v4, v0
	v_mov_b32_e32 v5, v0
	v_mov_b32_e32 v6, v0
	v_mov_b32_e32 v7, v0
	v_mov_b32_e32 v16, v0
	v_mov_b32_e32 v17, v0
	v_mov_b32_e32 v18, v0
	v_mov_b32_e32 v19, v0
	v_mov_b32_e32 v20, v0
	v_mov_b32_e32 v21, v0
	v_mov_b32_e32 v22, v0
	v_mov_b32_e32 v23, v0
	v_mov_b32_e32 v32, v0
	v_mov_b32_e32 v33, v0
	v_mov_b32_e32 v34, v0
	v_mov_b32_e32 v35, v0
	v_mov_b32_e32 v36, v0
	v_mov_b32_e32 v37, v0
	v_mov_b32_e32 v38, v0
	v_mov_b32_e32 v39, v0
	v_mov_b32_e32 v48, v0
	v_mov_b32_e32 v49, v0
	v_mov_b32_e32 v50, v0
	v_mov_b32_e32 v51, v0
	v_mov_b32_e32 v52, v0
	v_mov_b32_e32 v53, v0
	v_mov_b32_e32 v54, v0
	v_mov_b32_e32 v55, v0
	v_mov_b32_e32 v8, v0
	v_mov_b32_e32 v9, v0
	v_mov_b32_e32 v10, v0
	v_mov_b32_e32 v11, v0
	v_mov_b32_e32 v12, v0
	v_mov_b32_e32 v13, v0
	v_mov_b32_e32 v14, v0
	v_mov_b32_e32 v15, v0
	v_mov_b32_e32 v24, v0
	v_mov_b32_e32 v25, v0
	v_mov_b32_e32 v26, v0
	v_mov_b32_e32 v27, v0
	v_mov_b32_e32 v28, v0
	v_mov_b32_e32 v29, v0
	v_mov_b32_e32 v30, v0
	v_mov_b32_e32 v31, v0
	v_mov_b32_e32 v40, v0
	v_mov_b32_e32 v41, v0
	v_mov_b32_e32 v42, v0
	v_mov_b32_e32 v43, v0
	v_mov_b32_e32 v44, v0
	v_mov_b32_e32 v45, v0
	v_mov_b32_e32 v46, v0
	v_mov_b32_e32 v47, v0
	v_mov_b32_e32 v56, v0
	v_mov_b32_e32 v57, v0
	v_mov_b32_e32 v58, v0
	v_mov_b32_e32 v59, v0
	v_mov_b32_e32 v60, v0
	v_mov_b32_e32 v61, v0
	v_mov_b32_e32 v62, v0
	v_mov_b32_e32 v63, v0
	v_mov_b32_e32 v64, v0
	v_mov_b32_e32 v65, v0
	v_mov_b32_e32 v66, v0
	v_mov_b32_e32 v67, v0
	v_mov_b32_e32 v68, v0
	v_mov_b32_e32 v69, v0
	v_mov_b32_e32 v70, v0
	v_mov_b32_e32 v71, v0
	v_mov_b32_e32 v80, v0
	v_mov_b32_e32 v81, v0
	v_mov_b32_e32 v82, v0
	v_mov_b32_e32 v83, v0
	v_mov_b32_e32 v84, v0
	v_mov_b32_e32 v85, v0
	v_mov_b32_e32 v86, v0
	v_mov_b32_e32 v87, v0
	v_mov_b32_e32 v96, v0
	v_mov_b32_e32 v97, v0
	v_mov_b32_e32 v98, v0
	v_mov_b32_e32 v99, v0
	v_mov_b32_e32 v100, v0
	v_mov_b32_e32 v101, v0
	v_mov_b32_e32 v102, v0
	v_mov_b32_e32 v103, v0
	v_mov_b32_e32 v112, v0
	v_mov_b32_e32 v113, v0
	v_mov_b32_e32 v114, v0
	v_mov_b32_e32 v115, v0
	v_mov_b32_e32 v116, v0
	v_mov_b32_e32 v117, v0
	v_mov_b32_e32 v118, v0
	v_mov_b32_e32 v119, v0
	v_mov_b32_e32 v72, v0
	v_mov_b32_e32 v73, v0
	v_mov_b32_e32 v74, v0
	v_mov_b32_e32 v75, v0
	v_mov_b32_e32 v76, v0
	v_mov_b32_e32 v77, v0
	v_mov_b32_e32 v78, v0
	v_mov_b32_e32 v79, v0
	v_mov_b32_e32 v88, v0
	v_mov_b32_e32 v89, v0
	v_mov_b32_e32 v90, v0
	v_mov_b32_e32 v91, v0
	v_mov_b32_e32 v92, v0
	v_mov_b32_e32 v93, v0
	v_mov_b32_e32 v94, v0
	v_mov_b32_e32 v95, v0
	v_mov_b32_e32 v104, v0
	v_mov_b32_e32 v105, v0
	v_mov_b32_e32 v106, v0
	v_mov_b32_e32 v107, v0
	v_mov_b32_e32 v108, v0
	v_mov_b32_e32 v109, v0
	v_mov_b32_e32 v110, v0
	v_mov_b32_e32 v111, v0
	v_mov_b32_e32 v120, v0
	v_mov_b32_e32 v121, v0
	v_mov_b32_e32 v122, v0
	v_mov_b32_e32 v123, v0
	v_mov_b32_e32 v124, v0
	v_mov_b32_e32 v125, v0
	v_mov_b32_e32 v126, v0
	v_mov_b32_e32 v127, v0
	s_branch .LBB0_332
	.p2align 6

.LBB0_655:
	v_cndmask_b32_e64 v0, 0, 1, s[40:41]
	v_cmp_ne_u32_e64 s[6:7], 1, v0
	s_andn2_b64 vcc, exec, s[40:41]
	s_cbranch_vccnz .LBB0_657
	s_mov_b32 s24, s12
	s_mov_b32 s26, s47
	.p2align 6

.LBB0_1093:
	s_ashr_i32 s17, s16, 31
	s_lshl_b64 s[18:19], s[16:17], 20
	s_add_u32 s18, s34, s18
	s_addc_u32 s19, s35, s19
	s_and_b64 s[20:21], s[8:9], exec
	s_cselect_b32 s17, s19, s27
	s_cselect_b32 s23, s18, s26
	s_ashr_i32 s15, s14, 31
	s_lshl_b64 s[20:21], s[14:15], 20
	v_readlane_b32 s30, v237, 20
	v_readlane_b32 s31, v237, 21
	s_add_u32 s20, s30, s20
	s_addc_u32 s21, s31, s21
	s_and_b64 s[30:31], s[8:9], exec
	s_cselect_b32 s15, s21, s29
	s_cselect_b32 s45, s20, s28
	s_add_u32 s26, s26, 0x80080
	s_addc_u32 s27, s27, 0
	s_add_u32 s46, s28, 0x100
	v_mov_b32_e32 v0, 0
	s_addc_u32 s47, s29, 0
	s_mov_b32 s48, -2
	s_waitcnt lgkmcnt(0)
	v_mov_b32_e32 v1, v0
	v_mov_b32_e32 v2, v0
	v_mov_b32_e32 v3, v0
	v_mov_b32_e32 v4, v0
	v_mov_b32_e32 v5, v0
	v_mov_b32_e32 v6, v0
	v_mov_b32_e32 v7, v0
	v_mov_b32_e32 v16, v0
	v_mov_b32_e32 v17, v0
	v_mov_b32_e32 v18, v0
	v_mov_b32_e32 v19, v0
	v_mov_b32_e32 v20, v0
	v_mov_b32_e32 v21, v0
	v_mov_b32_e32 v22, v0
	v_mov_b32_e32 v23, v0
	v_mov_b32_e32 v32, v0
	v_mov_b32_e32 v33, v0
	v_mov_b32_e32 v34, v0
	v_mov_b32_e32 v35, v0
	v_mov_b32_e32 v36, v0
	v_mov_b32_e32 v37, v0
	v_mov_b32_e32 v38, v0
	v_mov_b32_e32 v39, v0
	v_mov_b32_e32 v48, v0
	v_mov_b32_e32 v49, v0
	v_mov_b32_e32 v50, v0
	v_mov_b32_e32 v51, v0
	v_mov_b32_e32 v52, v0
	v_mov_b32_e32 v53, v0
	v_mov_b32_e32 v54, v0
	v_mov_b32_e32 v55, v0
	v_mov_b32_e32 v8, v0
	v_mov_b32_e32 v9, v0
	v_mov_b32_e32 v10, v0
	v_mov_b32_e32 v11, v0
	v_mov_b32_e32 v12, v0
	v_mov_b32_e32 v13, v0
	v_mov_b32_e32 v14, v0
	v_mov_b32_e32 v15, v0
	v_mov_b32_e32 v24, v0
	v_mov_b32_e32 v25, v0
	v_mov_b32_e32 v26, v0
	v_mov_b32_e32 v27, v0
	v_mov_b32_e32 v28, v0
	v_mov_b32_e32 v29, v0
	v_mov_b32_e32 v30, v0
	v_mov_b32_e32 v31, v0
	v_mov_b32_e32 v40, v0
	v_mov_b32_e32 v41, v0
	v_mov_b32_e32 v42, v0
	v_mov_b32_e32 v43, v0
	v_mov_b32_e32 v44, v0
	v_mov_b32_e32 v45, v0
	v_mov_b32_e32 v46, v0
	v_mov_b32_e32 v47, v0
	v_mov_b32_e32 v56, v0
	v_mov_b32_e32 v57, v0
	v_mov_b32_e32 v58, v0
	v_mov_b32_e32 v59, v0
	v_mov_b32_e32 v60, v0
	v_mov_b32_e32 v61, v0
	v_mov_b32_e32 v62, v0
	v_mov_b32_e32 v63, v0
	v_mov_b32_e32 v64, v0
	v_mov_b32_e32 v65, v0
	v_mov_b32_e32 v66, v0
	v_mov_b32_e32 v67, v0
	v_mov_b32_e32 v68, v0
	v_mov_b32_e32 v69, v0
	v_mov_b32_e32 v70, v0
	v_mov_b32_e32 v71, v0
	v_mov_b32_e32 v80, v0
	v_mov_b32_e32 v81, v0
	v_mov_b32_e32 v82, v0
	v_mov_b32_e32 v83, v0
	v_mov_b32_e32 v84, v0
	v_mov_b32_e32 v85, v0
	v_mov_b32_e32 v86, v0
	v_mov_b32_e32 v87, v0
	v_mov_b32_e32 v96, v0
	v_mov_b32_e32 v97, v0
	v_mov_b32_e32 v98, v0
	v_mov_b32_e32 v99, v0
	v_mov_b32_e32 v100, v0
	v_mov_b32_e32 v101, v0
	v_mov_b32_e32 v102, v0
	v_mov_b32_e32 v103, v0
	v_mov_b32_e32 v112, v0
	v_mov_b32_e32 v113, v0
	v_mov_b32_e32 v114, v0
	v_mov_b32_e32 v115, v0
	v_mov_b32_e32 v116, v0
	v_mov_b32_e32 v117, v0
	v_mov_b32_e32 v118, v0
	v_mov_b32_e32 v119, v0
	v_mov_b32_e32 v72, v0
	v_mov_b32_e32 v73, v0
	v_mov_b32_e32 v74, v0
	v_mov_b32_e32 v75, v0
	v_mov_b32_e32 v76, v0
	v_mov_b32_e32 v77, v0
	v_mov_b32_e32 v78, v0
	v_mov_b32_e32 v79, v0
	v_mov_b32_e32 v88, v0
	v_mov_b32_e32 v89, v0
	v_mov_b32_e32 v90, v0
	v_mov_b32_e32 v91, v0
	v_mov_b32_e32 v92, v0
	v_mov_b32_e32 v93, v0
	v_mov_b32_e32 v94, v0
	v_mov_b32_e32 v95, v0
	v_mov_b32_e32 v104, v0
	v_mov_b32_e32 v105, v0
	v_mov_b32_e32 v106, v0
	v_mov_b32_e32 v107, v0
	v_mov_b32_e32 v108, v0
	v_mov_b32_e32 v109, v0
	v_mov_b32_e32 v110, v0
	v_mov_b32_e32 v111, v0
	v_mov_b32_e32 v120, v0
	v_mov_b32_e32 v121, v0
	v_mov_b32_e32 v122, v0
	v_mov_b32_e32 v123, v0
	v_mov_b32_e32 v124, v0
	v_mov_b32_e32 v125, v0
	v_mov_b32_e32 v126, v0
	v_mov_b32_e32 v127, v0
	.p2align 6

.LBB0_1177:
	s_ashr_i32 s23, s22, 31
	s_lshl_b64 s[24:25], s[22:23], 20
	s_add_u32 s24, s60, s24
	s_addc_u32 s25, s61, s25
	s_and_b64 s[26:27], s[8:9], exec
	s_cselect_b32 s23, s25, s35
	s_cselect_b32 s47, s24, s34
	s_ashr_i32 s21, s20, 31
	s_lshl_b64 s[26:27], s[20:21], 20
	s_add_u32 s26, s2, s26
	s_addc_u32 s27, s6, s27
	s_and_b64 s[48:49], s[8:9], exec
	s_cselect_b32 s21, s27, s31
	s_cselect_b32 s48, s26, s30
	v_lshl_add_u32 v152, s28, 8, v160
	s_add_u32 s28, s34, 0x80080
	s_addc_u32 s29, s35, 0
	v_ashrrev_i32_e32 v153, 31, v152
	s_add_u32 s49, s30, 0x100
	v_mov_b32_e32 v0, 0
	v_lshl_add_u64 v[154:155], v[152:153], 3, s[0:1]
	s_addc_u32 s50, s31, 0
	s_mov_b32 s51, -2
	v_mov_b32_e32 v1, v0
	v_mov_b32_e32 v2, v0
	v_mov_b32_e32 v3, v0
	v_mov_b32_e32 v4, v0
	v_mov_b32_e32 v5, v0
	v_mov_b32_e32 v6, v0
	v_mov_b32_e32 v7, v0
	v_mov_b32_e32 v16, v0
	v_mov_b32_e32 v17, v0
	v_mov_b32_e32 v18, v0
	v_mov_b32_e32 v19, v0
	v_mov_b32_e32 v20, v0
	v_mov_b32_e32 v21, v0
	v_mov_b32_e32 v22, v0
	v_mov_b32_e32 v23, v0
	v_mov_b32_e32 v32, v0
	v_mov_b32_e32 v33, v0
	v_mov_b32_e32 v34, v0
	v_mov_b32_e32 v35, v0
	v_mov_b32_e32 v36, v0
	v_mov_b32_e32 v37, v0
	v_mov_b32_e32 v38, v0
	v_mov_b32_e32 v39, v0
	v_mov_b32_e32 v48, v0
	v_mov_b32_e32 v49, v0
	v_mov_b32_e32 v50, v0
	v_mov_b32_e32 v51, v0
	v_mov_b32_e32 v52, v0
	v_mov_b32_e32 v53, v0
	v_mov_b32_e32 v54, v0
	v_mov_b32_e32 v55, v0
	v_mov_b32_e32 v8, v0
	v_mov_b32_e32 v9, v0
	v_mov_b32_e32 v10, v0
	v_mov_b32_e32 v11, v0
	v_mov_b32_e32 v12, v0
	v_mov_b32_e32 v13, v0
	v_mov_b32_e32 v14, v0
	v_mov_b32_e32 v15, v0
	v_mov_b32_e32 v24, v0
	v_mov_b32_e32 v25, v0
	v_mov_b32_e32 v26, v0
	v_mov_b32_e32 v27, v0
	v_mov_b32_e32 v28, v0
	v_mov_b32_e32 v29, v0
	v_mov_b32_e32 v30, v0
	v_mov_b32_e32 v31, v0
	v_mov_b32_e32 v40, v0
	v_mov_b32_e32 v41, v0
	v_mov_b32_e32 v42, v0
	v_mov_b32_e32 v43, v0
	v_mov_b32_e32 v44, v0
	v_mov_b32_e32 v45, v0
	v_mov_b32_e32 v46, v0
	v_mov_b32_e32 v47, v0
	v_mov_b32_e32 v56, v0
	v_mov_b32_e32 v57, v0
	v_mov_b32_e32 v58, v0
	v_mov_b32_e32 v59, v0
	v_mov_b32_e32 v60, v0
	v_mov_b32_e32 v61, v0
	v_mov_b32_e32 v62, v0
	v_mov_b32_e32 v63, v0
	v_mov_b32_e32 v64, v0
	v_mov_b32_e32 v65, v0
	v_mov_b32_e32 v66, v0
	v_mov_b32_e32 v67, v0
	v_mov_b32_e32 v68, v0
	v_mov_b32_e32 v69, v0
	v_mov_b32_e32 v70, v0
	v_mov_b32_e32 v71, v0
	v_mov_b32_e32 v80, v0
	v_mov_b32_e32 v81, v0
	v_mov_b32_e32 v82, v0
	v_mov_b32_e32 v83, v0
	v_mov_b32_e32 v84, v0
	v_mov_b32_e32 v85, v0
	v_mov_b32_e32 v86, v0
	v_mov_b32_e32 v87, v0
	v_mov_b32_e32 v96, v0
	v_mov_b32_e32 v97, v0
	v_mov_b32_e32 v98, v0
	v_mov_b32_e32 v99, v0
	v_mov_b32_e32 v100, v0
	v_mov_b32_e32 v101, v0
	v_mov_b32_e32 v102, v0
	v_mov_b32_e32 v103, v0
	v_mov_b32_e32 v112, v0
	v_mov_b32_e32 v113, v0
	v_mov_b32_e32 v114, v0
	v_mov_b32_e32 v115, v0
	v_mov_b32_e32 v116, v0
	v_mov_b32_e32 v117, v0
	v_mov_b32_e32 v118, v0
	v_mov_b32_e32 v119, v0
	v_mov_b32_e32 v72, v0
	v_mov_b32_e32 v73, v0
	v_mov_b32_e32 v74, v0
	v_mov_b32_e32 v75, v0
	v_mov_b32_e32 v76, v0
	v_mov_b32_e32 v77, v0
	v_mov_b32_e32 v78, v0
	v_mov_b32_e32 v79, v0
	v_mov_b32_e32 v88, v0
	v_mov_b32_e32 v89, v0
	v_mov_b32_e32 v90, v0
	v_mov_b32_e32 v91, v0
	v_mov_b32_e32 v92, v0
	v_mov_b32_e32 v93, v0
	v_mov_b32_e32 v94, v0
	v_mov_b32_e32 v95, v0
	v_mov_b32_e32 v104, v0
	v_mov_b32_e32 v105, v0
	v_mov_b32_e32 v106, v0
	v_mov_b32_e32 v107, v0
	v_mov_b32_e32 v108, v0
	v_mov_b32_e32 v109, v0
	v_mov_b32_e32 v110, v0
	v_mov_b32_e32 v111, v0
	v_mov_b32_e32 v120, v0
	v_mov_b32_e32 v121, v0
	v_mov_b32_e32 v122, v0
	v_mov_b32_e32 v123, v0
	v_mov_b32_e32 v124, v0
	v_mov_b32_e32 v125, v0
	v_mov_b32_e32 v126, v0
	v_mov_b32_e32 v127, v0
	s_branch .LBB0_1179
	.p2align 6

.LBB0_1293:
	s_add_u32 s44, s22, 0x100
	v_mov_b32_e32 v0, 0
	s_addc_u32 s45, s23, 0
	s_mov_b32 s46, -2
	s_waitcnt lgkmcnt(0)
	v_mov_b32_e32 v1, v0
	v_mov_b32_e32 v2, v0
	v_mov_b32_e32 v3, v0
	v_mov_b32_e32 v4, v0
	v_mov_b32_e32 v5, v0
	v_mov_b32_e32 v6, v0
	v_mov_b32_e32 v7, v0
	v_mov_b32_e32 v16, v0
	v_mov_b32_e32 v17, v0
	v_mov_b32_e32 v18, v0
	v_mov_b32_e32 v19, v0
	v_mov_b32_e32 v20, v0
	v_mov_b32_e32 v21, v0
	v_mov_b32_e32 v22, v0
	v_mov_b32_e32 v23, v0
	v_mov_b32_e32 v32, v0
	v_mov_b32_e32 v33, v0
	v_mov_b32_e32 v34, v0
	v_mov_b32_e32 v35, v0
	v_mov_b32_e32 v36, v0
	v_mov_b32_e32 v37, v0
	v_mov_b32_e32 v38, v0
	v_mov_b32_e32 v39, v0
	v_mov_b32_e32 v48, v0
	v_mov_b32_e32 v49, v0
	v_mov_b32_e32 v50, v0
	v_mov_b32_e32 v51, v0
	v_mov_b32_e32 v52, v0
	v_mov_b32_e32 v53, v0
	v_mov_b32_e32 v54, v0
	v_mov_b32_e32 v55, v0
	v_mov_b32_e32 v8, v0
	v_mov_b32_e32 v9, v0
	v_mov_b32_e32 v10, v0
	v_mov_b32_e32 v11, v0
	v_mov_b32_e32 v12, v0
	v_mov_b32_e32 v13, v0
	v_mov_b32_e32 v14, v0
	v_mov_b32_e32 v15, v0
	v_mov_b32_e32 v24, v0
	v_mov_b32_e32 v25, v0
	v_mov_b32_e32 v26, v0
	v_mov_b32_e32 v27, v0
	v_mov_b32_e32 v28, v0
	v_mov_b32_e32 v29, v0
	v_mov_b32_e32 v30, v0
	v_mov_b32_e32 v31, v0
	v_mov_b32_e32 v40, v0
	v_mov_b32_e32 v41, v0
	v_mov_b32_e32 v42, v0
	v_mov_b32_e32 v43, v0
	v_mov_b32_e32 v44, v0
	v_mov_b32_e32 v45, v0
	v_mov_b32_e32 v46, v0
	v_mov_b32_e32 v47, v0
	v_mov_b32_e32 v56, v0
	v_mov_b32_e32 v57, v0
	v_mov_b32_e32 v58, v0
	v_mov_b32_e32 v59, v0
	v_mov_b32_e32 v60, v0
	v_mov_b32_e32 v61, v0
	v_mov_b32_e32 v62, v0
	v_mov_b32_e32 v63, v0
	v_mov_b32_e32 v64, v0
	v_mov_b32_e32 v65, v0
	v_mov_b32_e32 v66, v0
	v_mov_b32_e32 v67, v0
	v_mov_b32_e32 v68, v0
	v_mov_b32_e32 v69, v0
	v_mov_b32_e32 v70, v0
	v_mov_b32_e32 v71, v0
	v_mov_b32_e32 v80, v0
	v_mov_b32_e32 v81, v0
	v_mov_b32_e32 v82, v0
	v_mov_b32_e32 v83, v0
	v_mov_b32_e32 v84, v0
	v_mov_b32_e32 v85, v0
	v_mov_b32_e32 v86, v0
	v_mov_b32_e32 v87, v0
	v_mov_b32_e32 v96, v0
	v_mov_b32_e32 v97, v0
	v_mov_b32_e32 v98, v0
	v_mov_b32_e32 v99, v0
	v_mov_b32_e32 v100, v0
	v_mov_b32_e32 v101, v0
	v_mov_b32_e32 v102, v0
	v_mov_b32_e32 v103, v0
	v_mov_b32_e32 v112, v0
	v_mov_b32_e32 v113, v0
	v_mov_b32_e32 v114, v0
	v_mov_b32_e32 v115, v0
	v_mov_b32_e32 v116, v0
	v_mov_b32_e32 v117, v0
	v_mov_b32_e32 v118, v0
	v_mov_b32_e32 v119, v0
	v_mov_b32_e32 v72, v0
	v_mov_b32_e32 v73, v0
	v_mov_b32_e32 v74, v0
	v_mov_b32_e32 v75, v0
	v_mov_b32_e32 v76, v0
	v_mov_b32_e32 v77, v0
	v_mov_b32_e32 v78, v0
	v_mov_b32_e32 v79, v0
	v_mov_b32_e32 v88, v0
	v_mov_b32_e32 v89, v0
	v_mov_b32_e32 v90, v0
	v_mov_b32_e32 v91, v0
	v_mov_b32_e32 v92, v0
	v_mov_b32_e32 v93, v0
	v_mov_b32_e32 v94, v0
	v_mov_b32_e32 v95, v0
	v_mov_b32_e32 v104, v0
	v_mov_b32_e32 v105, v0
	v_mov_b32_e32 v106, v0
	v_mov_b32_e32 v107, v0
	v_mov_b32_e32 v108, v0
	v_mov_b32_e32 v109, v0
	v_mov_b32_e32 v110, v0
	v_mov_b32_e32 v111, v0
	v_mov_b32_e32 v120, v0
	v_mov_b32_e32 v121, v0
	v_mov_b32_e32 v122, v0
	v_mov_b32_e32 v123, v0
	v_mov_b32_e32 v124, v0
	v_mov_b32_e32 v125, v0
	v_mov_b32_e32 v126, v0
	v_mov_b32_e32 v127, v0
	.p2align 6

.LBB0_1385:
	s_ashr_i32 s27, s26, 31
	s_lshl_b64 s[28:29], s[26:27], 20
	s_add_u32 s28, s60, s28
	s_addc_u32 s29, s61, s29
	s_and_b64 s[30:31], s[8:9], exec
	s_cselect_b32 s27, s29, s39
	s_cselect_b32 s53, s28, s38
	s_ashr_i32 s25, s24, 31
	s_lshl_b64 s[30:31], s[24:25], 20
	s_add_u32 s30, s50, s30
	s_addc_u32 s31, s51, s31
	s_and_b64 s[54:55], s[8:9], exec
	s_cselect_b32 s25, s31, s37
	s_cselect_b32 s54, s30, s36
	v_lshl_add_u32 v150, s34, 8, v158
	s_add_u32 s34, s38, 0x80080
	s_addc_u32 s35, s39, 0
	v_ashrrev_i32_e32 v151, 31, v150
	s_add_u32 s55, s36, 0x100
	v_mov_b32_e32 v0, 0
	v_lshl_add_u64 v[154:155], v[150:151], 3, s[4:5]
	s_addc_u32 s56, s37, 0
	s_mov_b32 s57, -2
	v_mov_b32_e32 v1, v0
	v_mov_b32_e32 v2, v0
	v_mov_b32_e32 v3, v0
	v_mov_b32_e32 v4, v0
	v_mov_b32_e32 v5, v0
	v_mov_b32_e32 v6, v0
	v_mov_b32_e32 v7, v0
	v_mov_b32_e32 v8, v0
	v_mov_b32_e32 v9, v0
	v_mov_b32_e32 v10, v0
	v_mov_b32_e32 v11, v0
	v_mov_b32_e32 v16, v0
	v_mov_b32_e32 v17, v0
	v_mov_b32_e32 v18, v0
	v_mov_b32_e32 v19, v0
	v_mov_b32_e32 v28, v0
	v_mov_b32_e32 v29, v0
	v_mov_b32_e32 v30, v0
	v_mov_b32_e32 v31, v0
	v_mov_b32_e32 v36, v0
	v_mov_b32_e32 v37, v0
	v_mov_b32_e32 v38, v0
	v_mov_b32_e32 v39, v0
	v_mov_b32_e32 v40, v0
	v_mov_b32_e32 v41, v0
	v_mov_b32_e32 v42, v0
	v_mov_b32_e32 v43, v0
	v_mov_b32_e32 v48, v0
	v_mov_b32_e32 v49, v0
	v_mov_b32_e32 v50, v0
	v_mov_b32_e32 v51, v0
	v_mov_b32_e32 v12, v0
	v_mov_b32_e32 v13, v0
	v_mov_b32_e32 v14, v0
	v_mov_b32_e32 v15, v0
	v_mov_b32_e32 v20, v0
	v_mov_b32_e32 v21, v0
	v_mov_b32_e32 v22, v0
	v_mov_b32_e32 v23, v0
	v_mov_b32_e32 v24, v0
	v_mov_b32_e32 v25, v0
	v_mov_b32_e32 v26, v0
	v_mov_b32_e32 v27, v0
	v_mov_b32_e32 v32, v0
	v_mov_b32_e32 v33, v0
	v_mov_b32_e32 v34, v0
	v_mov_b32_e32 v35, v0
	v_mov_b32_e32 v44, v0
	v_mov_b32_e32 v45, v0
	v_mov_b32_e32 v46, v0
	v_mov_b32_e32 v47, v0
	v_mov_b32_e32 v52, v0
	v_mov_b32_e32 v53, v0
	v_mov_b32_e32 v54, v0
	v_mov_b32_e32 v55, v0
	v_mov_b32_e32 v56, v0
	v_mov_b32_e32 v57, v0
	v_mov_b32_e32 v58, v0
	v_mov_b32_e32 v59, v0
	v_mov_b32_e32 v60, v0
	v_mov_b32_e32 v61, v0
	v_mov_b32_e32 v62, v0
	v_mov_b32_e32 v63, v0
	v_mov_b32_e32 v64, v0
	v_mov_b32_e32 v65, v0
	v_mov_b32_e32 v66, v0
	v_mov_b32_e32 v67, v0
	v_mov_b32_e32 v68, v0
	v_mov_b32_e32 v69, v0
	v_mov_b32_e32 v70, v0
	v_mov_b32_e32 v71, v0
	v_mov_b32_e32 v76, v0
	v_mov_b32_e32 v77, v0
	v_mov_b32_e32 v78, v0
	v_mov_b32_e32 v79, v0
	v_mov_b32_e32 v80, v0
	v_mov_b32_e32 v81, v0
	v_mov_b32_e32 v82, v0
	v_mov_b32_e32 v83, v0
	v_mov_b32_e32 v96, v0
	v_mov_b32_e32 v97, v0
	v_mov_b32_e32 v98, v0
	v_mov_b32_e32 v99, v0
	v_mov_b32_e32 v100, v0
	v_mov_b32_e32 v101, v0
	v_mov_b32_e32 v102, v0
	v_mov_b32_e32 v103, v0
	v_mov_b32_e32 v108, v0
	v_mov_b32_e32 v109, v0
	v_mov_b32_e32 v110, v0
	v_mov_b32_e32 v111, v0
	v_mov_b32_e32 v112, v0
	v_mov_b32_e32 v113, v0
	v_mov_b32_e32 v114, v0
	v_mov_b32_e32 v115, v0
	v_mov_b32_e32 v72, v0
	v_mov_b32_e32 v73, v0
	v_mov_b32_e32 v74, v0
	v_mov_b32_e32 v75, v0
	v_mov_b32_e32 v84, v0
	v_mov_b32_e32 v85, v0
	v_mov_b32_e32 v86, v0
	v_mov_b32_e32 v87, v0
	v_mov_b32_e32 v88, v0
	v_mov_b32_e32 v89, v0
	v_mov_b32_e32 v90, v0
	v_mov_b32_e32 v91, v0
	v_mov_b32_e32 v92, v0
	v_mov_b32_e32 v93, v0
	v_mov_b32_e32 v94, v0
	v_mov_b32_e32 v95, v0
	v_mov_b32_e32 v104, v0
	v_mov_b32_e32 v105, v0
	v_mov_b32_e32 v106, v0
	v_mov_b32_e32 v107, v0
	v_mov_b32_e32 v116, v0
	v_mov_b32_e32 v117, v0
	v_mov_b32_e32 v118, v0
	v_mov_b32_e32 v119, v0
	v_mov_b32_e32 v120, v0
	v_mov_b32_e32 v121, v0
	v_mov_b32_e32 v122, v0
	v_mov_b32_e32 v123, v0
	v_mov_b32_e32 v124, v0
	v_mov_b32_e32 v125, v0
	v_mov_b32_e32 v126, v0
	v_mov_b32_e32 v127, v0
	s_branch .LBB0_1387
	.p2align 6

.LBB0_1403:
	s_ashr_i32 s25, s24, 31
	s_lshl_b64 s[26:27], s[24:25], 20
	s_add_u32 s26, s60, s26
	s_addc_u32 s27, s61, s27
	s_and_b64 s[28:29], s[8:9], exec
	s_cselect_b32 s25, s27, s37
	s_cselect_b32 s49, s26, s36
	s_ashr_i32 s23, s22, 31
	s_lshl_b64 s[28:29], s[22:23], 20
	s_add_u32 s28, s2, s28
	s_addc_u32 s29, s6, s29
	s_and_b64 s[50:51], s[8:9], exec
	s_cselect_b32 s23, s29, s35
	s_cselect_b32 s50, s28, s34
	v_lshl_add_u32 v152, s30, 8, v160
	s_add_u32 s30, s36, 0x80080
	s_addc_u32 s31, s37, 0
	v_ashrrev_i32_e32 v153, 31, v152
	s_add_u32 s51, s34, 0x100
	v_mov_b32_e32 v0, 0
	v_lshl_add_u64 v[154:155], v[152:153], 3, s[4:5]
	s_addc_u32 s53, s35, 0
	s_mov_b32 s54, -2
	v_mov_b32_e32 v1, v0
	v_mov_b32_e32 v2, v0
	v_mov_b32_e32 v3, v0
	v_mov_b32_e32 v4, v0
	v_mov_b32_e32 v5, v0
	v_mov_b32_e32 v6, v0
	v_mov_b32_e32 v7, v0
	v_mov_b32_e32 v16, v0
	v_mov_b32_e32 v17, v0
	v_mov_b32_e32 v18, v0
	v_mov_b32_e32 v19, v0
	v_mov_b32_e32 v20, v0
	v_mov_b32_e32 v21, v0
	v_mov_b32_e32 v22, v0
	v_mov_b32_e32 v23, v0
	v_mov_b32_e32 v32, v0
	v_mov_b32_e32 v33, v0
	v_mov_b32_e32 v34, v0
	v_mov_b32_e32 v35, v0
	v_mov_b32_e32 v36, v0
	v_mov_b32_e32 v37, v0
	v_mov_b32_e32 v38, v0
	v_mov_b32_e32 v39, v0
	v_mov_b32_e32 v48, v0
	v_mov_b32_e32 v49, v0
	v_mov_b32_e32 v50, v0
	v_mov_b32_e32 v51, v0
	v_mov_b32_e32 v52, v0
	v_mov_b32_e32 v53, v0
	v_mov_b32_e32 v54, v0
	v_mov_b32_e32 v55, v0
	v_mov_b32_e32 v8, v0
	v_mov_b32_e32 v9, v0
	v_mov_b32_e32 v10, v0
	v_mov_b32_e32 v11, v0
	v_mov_b32_e32 v12, v0
	v_mov_b32_e32 v13, v0
	v_mov_b32_e32 v14, v0
	v_mov_b32_e32 v15, v0
	v_mov_b32_e32 v24, v0
	v_mov_b32_e32 v25, v0
	v_mov_b32_e32 v26, v0
	v_mov_b32_e32 v27, v0
	v_mov_b32_e32 v28, v0
	v_mov_b32_e32 v29, v0
	v_mov_b32_e32 v30, v0
	v_mov_b32_e32 v31, v0
	v_mov_b32_e32 v40, v0
	v_mov_b32_e32 v41, v0
	v_mov_b32_e32 v42, v0
	v_mov_b32_e32 v43, v0
	v_mov_b32_e32 v44, v0
	v_mov_b32_e32 v45, v0
	v_mov_b32_e32 v46, v0
	v_mov_b32_e32 v47, v0
	v_mov_b32_e32 v56, v0
	v_mov_b32_e32 v57, v0
	v_mov_b32_e32 v58, v0
	v_mov_b32_e32 v59, v0
	v_mov_b32_e32 v60, v0
	v_mov_b32_e32 v61, v0
	v_mov_b32_e32 v62, v0
	v_mov_b32_e32 v63, v0
	v_mov_b32_e32 v64, v0
	v_mov_b32_e32 v65, v0
	v_mov_b32_e32 v66, v0
	v_mov_b32_e32 v67, v0
	v_mov_b32_e32 v68, v0
	v_mov_b32_e32 v69, v0
	v_mov_b32_e32 v70, v0
	v_mov_b32_e32 v71, v0
	v_mov_b32_e32 v80, v0
	v_mov_b32_e32 v81, v0
	v_mov_b32_e32 v82, v0
	v_mov_b32_e32 v83, v0
	v_mov_b32_e32 v84, v0
	v_mov_b32_e32 v85, v0
	v_mov_b32_e32 v86, v0
	v_mov_b32_e32 v87, v0
	v_mov_b32_e32 v96, v0
	v_mov_b32_e32 v97, v0
	v_mov_b32_e32 v98, v0
	v_mov_b32_e32 v99, v0
	v_mov_b32_e32 v100, v0
	v_mov_b32_e32 v101, v0
	v_mov_b32_e32 v102, v0
	v_mov_b32_e32 v103, v0
	v_mov_b32_e32 v112, v0
	v_mov_b32_e32 v113, v0
	v_mov_b32_e32 v114, v0
	v_mov_b32_e32 v115, v0
	v_mov_b32_e32 v116, v0
	v_mov_b32_e32 v117, v0
	v_mov_b32_e32 v118, v0
	v_mov_b32_e32 v119, v0
	v_mov_b32_e32 v72, v0
	v_mov_b32_e32 v73, v0
	v_mov_b32_e32 v74, v0
	v_mov_b32_e32 v75, v0
	v_mov_b32_e32 v76, v0
	v_mov_b32_e32 v77, v0
	v_mov_b32_e32 v78, v0
	v_mov_b32_e32 v79, v0
	v_mov_b32_e32 v88, v0
	v_mov_b32_e32 v89, v0
	v_mov_b32_e32 v90, v0
	v_mov_b32_e32 v91, v0
	v_mov_b32_e32 v92, v0
	v_mov_b32_e32 v93, v0
	v_mov_b32_e32 v94, v0
	v_mov_b32_e32 v95, v0
	v_mov_b32_e32 v104, v0
	v_mov_b32_e32 v105, v0
	v_mov_b32_e32 v106, v0
	v_mov_b32_e32 v107, v0
	v_mov_b32_e32 v108, v0
	v_mov_b32_e32 v109, v0
	v_mov_b32_e32 v110, v0
	v_mov_b32_e32 v111, v0
	v_mov_b32_e32 v120, v0
	v_mov_b32_e32 v121, v0
	v_mov_b32_e32 v122, v0
	v_mov_b32_e32 v123, v0
	v_mov_b32_e32 v124, v0
	v_mov_b32_e32 v125, v0
	v_mov_b32_e32 v126, v0
	v_mov_b32_e32 v127, v0
	s_branch .LBB0_1405
	.p2align 6

.LBB0_1554:
	s_add_u32 s46, s22, 0x100
	v_mov_b32_e32 v0, 0
	s_addc_u32 s47, s23, 0
	s_mov_b32 s48, -2
	s_waitcnt lgkmcnt(0)
	v_mov_b32_e32 v1, v0
	v_mov_b32_e32 v2, v0
	v_mov_b32_e32 v3, v0
	v_mov_b32_e32 v4, v0
	v_mov_b32_e32 v5, v0
	v_mov_b32_e32 v6, v0
	v_mov_b32_e32 v7, v0
	v_mov_b32_e32 v16, v0
	v_mov_b32_e32 v17, v0
	v_mov_b32_e32 v18, v0
	v_mov_b32_e32 v19, v0
	v_mov_b32_e32 v20, v0
	v_mov_b32_e32 v21, v0
	v_mov_b32_e32 v22, v0
	v_mov_b32_e32 v23, v0
	v_mov_b32_e32 v32, v0
	v_mov_b32_e32 v33, v0
	v_mov_b32_e32 v34, v0
	v_mov_b32_e32 v35, v0
	v_mov_b32_e32 v36, v0
	v_mov_b32_e32 v37, v0
	v_mov_b32_e32 v38, v0
	v_mov_b32_e32 v39, v0
	v_mov_b32_e32 v48, v0
	v_mov_b32_e32 v49, v0
	v_mov_b32_e32 v50, v0
	v_mov_b32_e32 v51, v0
	v_mov_b32_e32 v52, v0
	v_mov_b32_e32 v53, v0
	v_mov_b32_e32 v54, v0
	v_mov_b32_e32 v55, v0
	v_mov_b32_e32 v8, v0
	v_mov_b32_e32 v9, v0
	v_mov_b32_e32 v10, v0
	v_mov_b32_e32 v11, v0
	v_mov_b32_e32 v12, v0
	v_mov_b32_e32 v13, v0
	v_mov_b32_e32 v14, v0
	v_mov_b32_e32 v15, v0
	v_mov_b32_e32 v24, v0
	v_mov_b32_e32 v25, v0
	v_mov_b32_e32 v26, v0
	v_mov_b32_e32 v27, v0
	v_mov_b32_e32 v28, v0
	v_mov_b32_e32 v29, v0
	v_mov_b32_e32 v30, v0
	v_mov_b32_e32 v31, v0
	v_mov_b32_e32 v40, v0
	v_mov_b32_e32 v41, v0
	v_mov_b32_e32 v42, v0
	v_mov_b32_e32 v43, v0
	v_mov_b32_e32 v44, v0
	v_mov_b32_e32 v45, v0
	v_mov_b32_e32 v46, v0
	v_mov_b32_e32 v47, v0
	v_mov_b32_e32 v56, v0
	v_mov_b32_e32 v57, v0
	v_mov_b32_e32 v58, v0
	v_mov_b32_e32 v59, v0
	v_mov_b32_e32 v60, v0
	v_mov_b32_e32 v61, v0
	v_mov_b32_e32 v62, v0
	v_mov_b32_e32 v63, v0
	v_mov_b32_e32 v64, v0
	v_mov_b32_e32 v65, v0
	v_mov_b32_e32 v66, v0
	v_mov_b32_e32 v67, v0
	v_mov_b32_e32 v68, v0
	v_mov_b32_e32 v69, v0
	v_mov_b32_e32 v70, v0
	v_mov_b32_e32 v71, v0
	v_mov_b32_e32 v80, v0
	v_mov_b32_e32 v81, v0
	v_mov_b32_e32 v82, v0
	v_mov_b32_e32 v83, v0
	v_mov_b32_e32 v84, v0
	v_mov_b32_e32 v85, v0
	v_mov_b32_e32 v86, v0
	v_mov_b32_e32 v87, v0
	v_mov_b32_e32 v96, v0
	v_mov_b32_e32 v97, v0
	v_mov_b32_e32 v98, v0
	v_mov_b32_e32 v99, v0
	v_mov_b32_e32 v100, v0
	v_mov_b32_e32 v101, v0
	v_mov_b32_e32 v102, v0
	v_mov_b32_e32 v103, v0
	v_mov_b32_e32 v112, v0
	v_mov_b32_e32 v113, v0
	v_mov_b32_e32 v114, v0
	v_mov_b32_e32 v115, v0
	v_mov_b32_e32 v116, v0
	v_mov_b32_e32 v117, v0
	v_mov_b32_e32 v118, v0
	v_mov_b32_e32 v119, v0
	v_mov_b32_e32 v72, v0
	v_mov_b32_e32 v73, v0
	v_mov_b32_e32 v74, v0
	v_mov_b32_e32 v75, v0
	v_mov_b32_e32 v76, v0
	v_mov_b32_e32 v77, v0
	v_mov_b32_e32 v78, v0
	v_mov_b32_e32 v79, v0
	v_mov_b32_e32 v88, v0
	v_mov_b32_e32 v89, v0
	v_mov_b32_e32 v90, v0
	v_mov_b32_e32 v91, v0
	v_mov_b32_e32 v92, v0
	v_mov_b32_e32 v93, v0
	v_mov_b32_e32 v94, v0
	v_mov_b32_e32 v95, v0
	v_mov_b32_e32 v104, v0
	v_mov_b32_e32 v105, v0
	v_mov_b32_e32 v106, v0
	v_mov_b32_e32 v107, v0
	v_mov_b32_e32 v108, v0
	v_mov_b32_e32 v109, v0
	v_mov_b32_e32 v110, v0
	v_mov_b32_e32 v111, v0
	v_mov_b32_e32 v120, v0
	v_mov_b32_e32 v121, v0
	v_mov_b32_e32 v122, v0
	v_mov_b32_e32 v123, v0
	v_mov_b32_e32 v124, v0
	v_mov_b32_e32 v125, v0
	v_mov_b32_e32 v126, v0
	v_mov_b32_e32 v127, v0
	.p2align 6

.LBB0_1646:
	s_ashr_i32 s29, s28, 31
	s_lshl_b64 s[30:31], s[28:29], 20
	s_add_u32 s30, s60, s30
	s_addc_u32 s31, s61, s31
	s_and_b64 s[34:35], s[4:5], exec
	s_cselect_b32 s29, s31, s45
	s_cselect_b32 s63, s30, s44
	s_ashr_i32 s27, s26, 31
	s_lshl_b64 s[34:35], s[26:27], 20
	s_add_u32 s34, s7, s34
	s_addc_u32 s35, s15, s35
	s_and_b64 s[64:65], s[4:5], exec
	s_cselect_b32 s27, s35, s43
	s_cselect_b32 s64, s34, s42
	v_lshl_add_u32 v152, s40, 8, v158
	s_add_u32 s40, s44, 0x80080
	s_addc_u32 s41, s45, 0
	v_ashrrev_i32_e32 v153, 31, v152
	s_add_u32 s65, s42, 0x100
	v_mov_b32_e32 v0, 0
	v_lshl_add_u64 v[154:155], v[152:153], 3, s[10:11]
	s_addc_u32 s66, s43, 0
	s_mov_b32 s67, -2
	v_mov_b32_e32 v1, v0
	v_mov_b32_e32 v2, v0
	v_mov_b32_e32 v3, v0
	v_mov_b32_e32 v4, v0
	v_mov_b32_e32 v5, v0
	v_mov_b32_e32 v6, v0
	v_mov_b32_e32 v7, v0
	v_mov_b32_e32 v8, v0
	v_mov_b32_e32 v9, v0
	v_mov_b32_e32 v10, v0
	v_mov_b32_e32 v11, v0
	v_mov_b32_e32 v16, v0
	v_mov_b32_e32 v17, v0
	v_mov_b32_e32 v18, v0
	v_mov_b32_e32 v19, v0
	v_mov_b32_e32 v28, v0
	v_mov_b32_e32 v29, v0
	v_mov_b32_e32 v30, v0
	v_mov_b32_e32 v31, v0
	v_mov_b32_e32 v36, v0
	v_mov_b32_e32 v37, v0
	v_mov_b32_e32 v38, v0
	v_mov_b32_e32 v39, v0
	v_mov_b32_e32 v40, v0
	v_mov_b32_e32 v41, v0
	v_mov_b32_e32 v42, v0
	v_mov_b32_e32 v43, v0
	v_mov_b32_e32 v48, v0
	v_mov_b32_e32 v49, v0
	v_mov_b32_e32 v50, v0
	v_mov_b32_e32 v51, v0
	v_mov_b32_e32 v12, v0
	v_mov_b32_e32 v13, v0
	v_mov_b32_e32 v14, v0
	v_mov_b32_e32 v15, v0
	v_mov_b32_e32 v20, v0
	v_mov_b32_e32 v21, v0
	v_mov_b32_e32 v22, v0
	v_mov_b32_e32 v23, v0
	v_mov_b32_e32 v24, v0
	v_mov_b32_e32 v25, v0
	v_mov_b32_e32 v26, v0
	v_mov_b32_e32 v27, v0
	v_mov_b32_e32 v32, v0
	v_mov_b32_e32 v33, v0
	v_mov_b32_e32 v34, v0
	v_mov_b32_e32 v35, v0
	v_mov_b32_e32 v44, v0
	v_mov_b32_e32 v45, v0
	v_mov_b32_e32 v46, v0
	v_mov_b32_e32 v47, v0
	v_mov_b32_e32 v52, v0
	v_mov_b32_e32 v53, v0
	v_mov_b32_e32 v54, v0
	v_mov_b32_e32 v55, v0
	v_mov_b32_e32 v56, v0
	v_mov_b32_e32 v57, v0
	v_mov_b32_e32 v58, v0
	v_mov_b32_e32 v59, v0
	v_mov_b32_e32 v60, v0
	v_mov_b32_e32 v61, v0
	v_mov_b32_e32 v62, v0
	v_mov_b32_e32 v63, v0
	v_mov_b32_e32 v64, v0
	v_mov_b32_e32 v65, v0
	v_mov_b32_e32 v66, v0
	v_mov_b32_e32 v67, v0
	v_mov_b32_e32 v68, v0
	v_mov_b32_e32 v69, v0
	v_mov_b32_e32 v70, v0
	v_mov_b32_e32 v71, v0
	v_mov_b32_e32 v76, v0
	v_mov_b32_e32 v77, v0
	v_mov_b32_e32 v78, v0
	v_mov_b32_e32 v79, v0
	v_mov_b32_e32 v80, v0
	v_mov_b32_e32 v81, v0
	v_mov_b32_e32 v82, v0
	v_mov_b32_e32 v83, v0
	v_mov_b32_e32 v96, v0
	v_mov_b32_e32 v97, v0
	v_mov_b32_e32 v98, v0
	v_mov_b32_e32 v99, v0
	v_mov_b32_e32 v100, v0
	v_mov_b32_e32 v101, v0
	v_mov_b32_e32 v102, v0
	v_mov_b32_e32 v103, v0
	v_mov_b32_e32 v108, v0
	v_mov_b32_e32 v109, v0
	v_mov_b32_e32 v110, v0
	v_mov_b32_e32 v111, v0
	v_mov_b32_e32 v112, v0
	v_mov_b32_e32 v113, v0
	v_mov_b32_e32 v114, v0
	v_mov_b32_e32 v115, v0
	v_mov_b32_e32 v72, v0
	v_mov_b32_e32 v73, v0
	v_mov_b32_e32 v74, v0
	v_mov_b32_e32 v75, v0
	v_mov_b32_e32 v84, v0
	v_mov_b32_e32 v85, v0
	v_mov_b32_e32 v86, v0
	v_mov_b32_e32 v87, v0
	v_mov_b32_e32 v88, v0
	v_mov_b32_e32 v89, v0
	v_mov_b32_e32 v90, v0
	v_mov_b32_e32 v91, v0
	v_mov_b32_e32 v92, v0
	v_mov_b32_e32 v93, v0
	v_mov_b32_e32 v94, v0
	v_mov_b32_e32 v95, v0
	v_mov_b32_e32 v104, v0
	v_mov_b32_e32 v105, v0
	v_mov_b32_e32 v106, v0
	v_mov_b32_e32 v107, v0
	v_mov_b32_e32 v116, v0
	v_mov_b32_e32 v117, v0
	v_mov_b32_e32 v118, v0
	v_mov_b32_e32 v119, v0
	v_mov_b32_e32 v120, v0
	v_mov_b32_e32 v121, v0
	v_mov_b32_e32 v122, v0
	v_mov_b32_e32 v123, v0
	v_mov_b32_e32 v124, v0
	v_mov_b32_e32 v125, v0
	v_mov_b32_e32 v126, v0
	v_mov_b32_e32 v127, v0
	s_branch .LBB0_1648
	.p2align 6

.LBB0_1864:
	s_ashr_i32 s19, s18, 31
	s_lshl_b64 s[20:21], s[18:19], 20
	s_add_u32 s20, s2, s20
	s_addc_u32 s21, s6, s21
	s_and_b64 s[22:23], s[8:9], exec
	s_cselect_b32 s19, s21, s29
	s_cselect_b32 s25, s20, s28
	s_ashr_i32 s17, s16, 31
	s_lshl_b64 s[22:23], s[16:17], 20
	s_add_u32 s22, s36, s22
	s_addc_u32 s23, s37, s23
	s_and_b64 s[34:35], s[8:9], exec
	s_cselect_b32 s17, s23, s31
	s_cselect_b32 s47, s22, s30
	s_add_u32 s28, s28, 0x80080
	s_addc_u32 s29, s29, 0
	s_add_u32 s48, s30, 0x100
	v_mov_b32_e32 v0, 0
	s_addc_u32 s49, s31, 0
	s_mov_b32 s50, -2
	s_waitcnt lgkmcnt(0)
	v_mov_b32_e32 v1, v0
	v_mov_b32_e32 v2, v0
	v_mov_b32_e32 v3, v0
	v_mov_b32_e32 v4, v0
	v_mov_b32_e32 v5, v0
	v_mov_b32_e32 v6, v0
	v_mov_b32_e32 v7, v0
	v_mov_b32_e32 v16, v0
	v_mov_b32_e32 v17, v0
	v_mov_b32_e32 v18, v0
	v_mov_b32_e32 v19, v0
	v_mov_b32_e32 v20, v0
	v_mov_b32_e32 v21, v0
	v_mov_b32_e32 v22, v0
	v_mov_b32_e32 v23, v0
	v_mov_b32_e32 v32, v0
	v_mov_b32_e32 v33, v0
	v_mov_b32_e32 v34, v0
	v_mov_b32_e32 v35, v0
	v_mov_b32_e32 v36, v0
	v_mov_b32_e32 v37, v0
	v_mov_b32_e32 v38, v0
	v_mov_b32_e32 v39, v0
	v_mov_b32_e32 v48, v0
	v_mov_b32_e32 v49, v0
	v_mov_b32_e32 v50, v0
	v_mov_b32_e32 v51, v0
	v_mov_b32_e32 v52, v0
	v_mov_b32_e32 v53, v0
	v_mov_b32_e32 v54, v0
	v_mov_b32_e32 v55, v0
	v_mov_b32_e32 v8, v0
	v_mov_b32_e32 v9, v0
	v_mov_b32_e32 v10, v0
	v_mov_b32_e32 v11, v0
	v_mov_b32_e32 v12, v0
	v_mov_b32_e32 v13, v0
	v_mov_b32_e32 v14, v0
	v_mov_b32_e32 v15, v0
	v_mov_b32_e32 v24, v0
	v_mov_b32_e32 v25, v0
	v_mov_b32_e32 v26, v0
	v_mov_b32_e32 v27, v0
	v_mov_b32_e32 v28, v0
	v_mov_b32_e32 v29, v0
	v_mov_b32_e32 v30, v0
	v_mov_b32_e32 v31, v0
	v_mov_b32_e32 v40, v0
	v_mov_b32_e32 v41, v0
	v_mov_b32_e32 v42, v0
	v_mov_b32_e32 v43, v0
	v_mov_b32_e32 v44, v0
	v_mov_b32_e32 v45, v0
	v_mov_b32_e32 v46, v0
	v_mov_b32_e32 v47, v0
	v_mov_b32_e32 v56, v0
	v_mov_b32_e32 v57, v0
	v_mov_b32_e32 v58, v0
	v_mov_b32_e32 v59, v0
	v_mov_b32_e32 v60, v0
	v_mov_b32_e32 v61, v0
	v_mov_b32_e32 v62, v0
	v_mov_b32_e32 v63, v0
	v_mov_b32_e32 v64, v0
	v_mov_b32_e32 v65, v0
	v_mov_b32_e32 v66, v0
	v_mov_b32_e32 v67, v0
	v_mov_b32_e32 v68, v0
	v_mov_b32_e32 v69, v0
	v_mov_b32_e32 v70, v0
	v_mov_b32_e32 v71, v0
	v_mov_b32_e32 v80, v0
	v_mov_b32_e32 v81, v0
	v_mov_b32_e32 v82, v0
	v_mov_b32_e32 v83, v0
	v_mov_b32_e32 v84, v0
	v_mov_b32_e32 v85, v0
	v_mov_b32_e32 v86, v0
	v_mov_b32_e32 v87, v0
	v_mov_b32_e32 v96, v0
	v_mov_b32_e32 v97, v0
	v_mov_b32_e32 v98, v0
	v_mov_b32_e32 v99, v0
	v_mov_b32_e32 v100, v0
	v_mov_b32_e32 v101, v0
	v_mov_b32_e32 v102, v0
	v_mov_b32_e32 v103, v0
	v_mov_b32_e32 v112, v0
	v_mov_b32_e32 v113, v0
	v_mov_b32_e32 v114, v0
	v_mov_b32_e32 v115, v0
	v_mov_b32_e32 v116, v0
	v_mov_b32_e32 v117, v0
	v_mov_b32_e32 v118, v0
	v_mov_b32_e32 v119, v0
	v_mov_b32_e32 v72, v0
	v_mov_b32_e32 v73, v0
	v_mov_b32_e32 v74, v0
	v_mov_b32_e32 v75, v0
	v_mov_b32_e32 v76, v0
	v_mov_b32_e32 v77, v0
	v_mov_b32_e32 v78, v0
	v_mov_b32_e32 v79, v0
	v_mov_b32_e32 v88, v0
	v_mov_b32_e32 v89, v0
	v_mov_b32_e32 v90, v0
	v_mov_b32_e32 v91, v0
	v_mov_b32_e32 v92, v0
	v_mov_b32_e32 v93, v0
	v_mov_b32_e32 v94, v0
	v_mov_b32_e32 v95, v0
	v_mov_b32_e32 v104, v0
	v_mov_b32_e32 v105, v0
	v_mov_b32_e32 v106, v0
	v_mov_b32_e32 v107, v0
	v_mov_b32_e32 v108, v0
	v_mov_b32_e32 v109, v0
	v_mov_b32_e32 v110, v0
	v_mov_b32_e32 v111, v0
	v_mov_b32_e32 v120, v0
	v_mov_b32_e32 v121, v0
	v_mov_b32_e32 v122, v0
	v_mov_b32_e32 v123, v0
	v_mov_b32_e32 v124, v0
	v_mov_b32_e32 v125, v0
	v_mov_b32_e32 v126, v0
	v_mov_b32_e32 v127, v0
	.p2align 6

.LBB0_1948:
	s_ashr_i32 s21, s20, 31
	s_lshl_b64 s[22:23], s[20:21], 20
	s_add_u32 s22, s60, s22
	s_addc_u32 s23, s61, s23
	s_and_b64 s[24:25], s[4:5], exec
	s_cselect_b32 s21, s23, s31
	s_cselect_b32 s47, s22, s30
	s_ashr_i32 s19, s18, 31
	s_lshl_b64 s[24:25], s[18:19], 20
	s_add_u32 s24, s2, s24
	s_addc_u32 s25, s13, s25
	s_and_b64 s[48:49], s[4:5], exec
	s_cselect_b32 s19, s25, s29
	s_cselect_b32 s48, s24, s28
	v_lshl_add_u32 v152, s26, 8, v160
	s_add_u32 s26, s30, 0x80080
	s_addc_u32 s27, s31, 0
	v_ashrrev_i32_e32 v153, 31, v152
	s_add_u32 s49, s28, 0x100
	v_mov_b32_e32 v0, 0
	v_lshl_add_u64 v[154:155], v[152:153], 3, s[0:1]
	s_addc_u32 s50, s29, 0
	s_mov_b32 s51, -2
	v_mov_b32_e32 v1, v0
	v_mov_b32_e32 v2, v0
	v_mov_b32_e32 v3, v0
	v_mov_b32_e32 v4, v0
	v_mov_b32_e32 v5, v0
	v_mov_b32_e32 v6, v0
	v_mov_b32_e32 v7, v0
	v_mov_b32_e32 v16, v0
	v_mov_b32_e32 v17, v0
	v_mov_b32_e32 v18, v0
	v_mov_b32_e32 v19, v0
	v_mov_b32_e32 v20, v0
	v_mov_b32_e32 v21, v0
	v_mov_b32_e32 v22, v0
	v_mov_b32_e32 v23, v0
	v_mov_b32_e32 v32, v0
	v_mov_b32_e32 v33, v0
	v_mov_b32_e32 v34, v0
	v_mov_b32_e32 v35, v0
	v_mov_b32_e32 v36, v0
	v_mov_b32_e32 v37, v0
	v_mov_b32_e32 v38, v0
	v_mov_b32_e32 v39, v0
	v_mov_b32_e32 v48, v0
	v_mov_b32_e32 v49, v0
	v_mov_b32_e32 v50, v0
	v_mov_b32_e32 v51, v0
	v_mov_b32_e32 v52, v0
	v_mov_b32_e32 v53, v0
	v_mov_b32_e32 v54, v0
	v_mov_b32_e32 v55, v0
	v_mov_b32_e32 v8, v0
	v_mov_b32_e32 v9, v0
	v_mov_b32_e32 v10, v0
	v_mov_b32_e32 v11, v0
	v_mov_b32_e32 v12, v0
	v_mov_b32_e32 v13, v0
	v_mov_b32_e32 v14, v0
	v_mov_b32_e32 v15, v0
	v_mov_b32_e32 v24, v0
	v_mov_b32_e32 v25, v0
	v_mov_b32_e32 v26, v0
	v_mov_b32_e32 v27, v0
	v_mov_b32_e32 v28, v0
	v_mov_b32_e32 v29, v0
	v_mov_b32_e32 v30, v0
	v_mov_b32_e32 v31, v0
	v_mov_b32_e32 v40, v0
	v_mov_b32_e32 v41, v0
	v_mov_b32_e32 v42, v0
	v_mov_b32_e32 v43, v0
	v_mov_b32_e32 v44, v0
	v_mov_b32_e32 v45, v0
	v_mov_b32_e32 v46, v0
	v_mov_b32_e32 v47, v0
	v_mov_b32_e32 v56, v0
	v_mov_b32_e32 v57, v0
	v_mov_b32_e32 v58, v0
	v_mov_b32_e32 v59, v0
	v_mov_b32_e32 v60, v0
	v_mov_b32_e32 v61, v0
	v_mov_b32_e32 v62, v0
	v_mov_b32_e32 v63, v0
	v_mov_b32_e32 v64, v0
	v_mov_b32_e32 v65, v0
	v_mov_b32_e32 v66, v0
	v_mov_b32_e32 v67, v0
	v_mov_b32_e32 v68, v0
	v_mov_b32_e32 v69, v0
	v_mov_b32_e32 v70, v0
	v_mov_b32_e32 v71, v0
	v_mov_b32_e32 v80, v0
	v_mov_b32_e32 v81, v0
	v_mov_b32_e32 v82, v0
	v_mov_b32_e32 v83, v0
	v_mov_b32_e32 v84, v0
	v_mov_b32_e32 v85, v0
	v_mov_b32_e32 v86, v0
	v_mov_b32_e32 v87, v0
	v_mov_b32_e32 v96, v0
	v_mov_b32_e32 v97, v0
	v_mov_b32_e32 v98, v0
	v_mov_b32_e32 v99, v0
	v_mov_b32_e32 v100, v0
	v_mov_b32_e32 v101, v0
	v_mov_b32_e32 v102, v0
	v_mov_b32_e32 v103, v0
	v_mov_b32_e32 v112, v0
	v_mov_b32_e32 v113, v0
	v_mov_b32_e32 v114, v0
	v_mov_b32_e32 v115, v0
	v_mov_b32_e32 v116, v0
	v_mov_b32_e32 v117, v0
	v_mov_b32_e32 v118, v0
	v_mov_b32_e32 v119, v0
	v_mov_b32_e32 v72, v0
	v_mov_b32_e32 v73, v0
	v_mov_b32_e32 v74, v0
	v_mov_b32_e32 v75, v0
	v_mov_b32_e32 v76, v0
	v_mov_b32_e32 v77, v0
	v_mov_b32_e32 v78, v0
	v_mov_b32_e32 v79, v0
	v_mov_b32_e32 v88, v0
	v_mov_b32_e32 v89, v0
	v_mov_b32_e32 v90, v0
	v_mov_b32_e32 v91, v0
	v_mov_b32_e32 v92, v0
	v_mov_b32_e32 v93, v0
	v_mov_b32_e32 v94, v0
	v_mov_b32_e32 v95, v0
	v_mov_b32_e32 v104, v0
	v_mov_b32_e32 v105, v0
	v_mov_b32_e32 v106, v0
	v_mov_b32_e32 v107, v0
	v_mov_b32_e32 v108, v0
	v_mov_b32_e32 v109, v0
	v_mov_b32_e32 v110, v0
	v_mov_b32_e32 v111, v0
	v_mov_b32_e32 v120, v0
	v_mov_b32_e32 v121, v0
	v_mov_b32_e32 v122, v0
	v_mov_b32_e32 v123, v0
	v_mov_b32_e32 v124, v0
	v_mov_b32_e32 v125, v0
	v_mov_b32_e32 v126, v0
	v_mov_b32_e32 v127, v0
	s_branch .LBB0_1950
	.p2align 6

.LBB0_2043:
	s_add_u32 s54, s34, 0x100
	v_mov_b32_e32 v0, 0
	s_addc_u32 s55, s35, 0
	s_mov_b32 s56, -2
	s_waitcnt lgkmcnt(0)
	v_mov_b32_e32 v1, v0
	v_mov_b32_e32 v2, v0
	v_mov_b32_e32 v3, v0
	v_mov_b32_e32 v4, v0
	v_mov_b32_e32 v5, v0
	v_mov_b32_e32 v6, v0
	v_mov_b32_e32 v7, v0
	v_mov_b32_e32 v16, v0
	v_mov_b32_e32 v17, v0
	v_mov_b32_e32 v18, v0
	v_mov_b32_e32 v19, v0
	v_mov_b32_e32 v20, v0
	v_mov_b32_e32 v21, v0
	v_mov_b32_e32 v22, v0
	v_mov_b32_e32 v23, v0
	v_mov_b32_e32 v32, v0
	v_mov_b32_e32 v33, v0
	v_mov_b32_e32 v34, v0
	v_mov_b32_e32 v35, v0
	v_mov_b32_e32 v36, v0
	v_mov_b32_e32 v37, v0
	v_mov_b32_e32 v38, v0
	v_mov_b32_e32 v39, v0
	v_mov_b32_e32 v48, v0
	v_mov_b32_e32 v49, v0
	v_mov_b32_e32 v50, v0
	v_mov_b32_e32 v51, v0
	v_mov_b32_e32 v52, v0
	v_mov_b32_e32 v53, v0
	v_mov_b32_e32 v54, v0
	v_mov_b32_e32 v55, v0
	v_mov_b32_e32 v8, v0
	v_mov_b32_e32 v9, v0
	v_mov_b32_e32 v10, v0
	v_mov_b32_e32 v11, v0
	v_mov_b32_e32 v12, v0
	v_mov_b32_e32 v13, v0
	v_mov_b32_e32 v14, v0
	v_mov_b32_e32 v15, v0
	v_mov_b32_e32 v24, v0
	v_mov_b32_e32 v25, v0
	v_mov_b32_e32 v26, v0
	v_mov_b32_e32 v27, v0
	v_mov_b32_e32 v28, v0
	v_mov_b32_e32 v29, v0
	v_mov_b32_e32 v30, v0
	v_mov_b32_e32 v31, v0
	v_mov_b32_e32 v40, v0
	v_mov_b32_e32 v41, v0
	v_mov_b32_e32 v42, v0
	v_mov_b32_e32 v43, v0
	v_mov_b32_e32 v44, v0
	v_mov_b32_e32 v45, v0
	v_mov_b32_e32 v46, v0
	v_mov_b32_e32 v47, v0
	v_mov_b32_e32 v56, v0
	v_mov_b32_e32 v57, v0
	v_mov_b32_e32 v58, v0
	v_mov_b32_e32 v59, v0
	v_mov_b32_e32 v60, v0
	v_mov_b32_e32 v61, v0
	v_mov_b32_e32 v62, v0
	v_mov_b32_e32 v63, v0
	v_mov_b32_e32 v64, v0
	v_mov_b32_e32 v65, v0
	v_mov_b32_e32 v66, v0
	v_mov_b32_e32 v67, v0
	v_mov_b32_e32 v68, v0
	v_mov_b32_e32 v69, v0
	v_mov_b32_e32 v70, v0
	v_mov_b32_e32 v71, v0
	v_mov_b32_e32 v80, v0
	v_mov_b32_e32 v81, v0
	v_mov_b32_e32 v82, v0
	v_mov_b32_e32 v83, v0
	v_mov_b32_e32 v84, v0
	v_mov_b32_e32 v85, v0
	v_mov_b32_e32 v86, v0
	v_mov_b32_e32 v87, v0
	v_mov_b32_e32 v96, v0
	v_mov_b32_e32 v97, v0
	v_mov_b32_e32 v98, v0
	v_mov_b32_e32 v99, v0
	v_mov_b32_e32 v100, v0
	v_mov_b32_e32 v101, v0
	v_mov_b32_e32 v102, v0
	v_mov_b32_e32 v103, v0
	v_mov_b32_e32 v112, v0
	v_mov_b32_e32 v113, v0
	v_mov_b32_e32 v114, v0
	v_mov_b32_e32 v115, v0
	v_mov_b32_e32 v116, v0
	v_mov_b32_e32 v117, v0
	v_mov_b32_e32 v118, v0
	v_mov_b32_e32 v119, v0
	v_mov_b32_e32 v72, v0
	v_mov_b32_e32 v73, v0
	v_mov_b32_e32 v74, v0
	v_mov_b32_e32 v75, v0
	v_mov_b32_e32 v76, v0
	v_mov_b32_e32 v77, v0
	v_mov_b32_e32 v78, v0
	v_mov_b32_e32 v79, v0
	v_mov_b32_e32 v88, v0
	v_mov_b32_e32 v89, v0
	v_mov_b32_e32 v90, v0
	v_mov_b32_e32 v91, v0
	v_mov_b32_e32 v92, v0
	v_mov_b32_e32 v93, v0
	v_mov_b32_e32 v94, v0
	v_mov_b32_e32 v95, v0
	v_mov_b32_e32 v104, v0
	v_mov_b32_e32 v105, v0
	v_mov_b32_e32 v106, v0
	v_mov_b32_e32 v107, v0
	v_mov_b32_e32 v108, v0
	v_mov_b32_e32 v109, v0
	v_mov_b32_e32 v110, v0
	v_mov_b32_e32 v111, v0
	v_mov_b32_e32 v120, v0
	v_mov_b32_e32 v121, v0
	v_mov_b32_e32 v122, v0
	v_mov_b32_e32 v123, v0
	v_mov_b32_e32 v124, v0
	v_mov_b32_e32 v125, v0
	v_mov_b32_e32 v126, v0
	v_mov_b32_e32 v127, v0
	.p2align 6
